# counted wait in the out-proj / MLP-out phase prologues: vmcnt(8) leaves the eight stage DMAs in flight instead of a full drain
# speedup vs baseline: 1.0016x; 1.0016x over previous
; __device__ __forceinline__ int prow0(int pm) { return (pm >> 4) * LP + PADR + (pm & 15) * 256; }
;     __device__ __forceinline__ void prep(int pm, int par, LAS unsigned char* lds) const { if (fold) prep_rowstats(stat, pm, par, lds); }
;     __device__ __forceinline__ void prep(int pm, int par, LAS unsigned char* lds) const { if (!ident) prep_rowstats(stat, pm, par, lds); }
;     __device__ __forceinline__ void prep(int pm, int par, LAS unsigned char* lds) const { prep_rowstats(stat, pm, par, lds); }
; #define G_STAGE(bufoff, gbase) do { _Pragma("unroll") for (int _i = 0; _i < 2; ++_i) \
;         __builtin_amdgcn_global_load_lds((const unsigned*)((const char*)(gbase) + voff[_i]), (LAS unsigned*)(lds + (bufoff) + ldsw + _i * 8192), 16, 0, 0); } while (0)
; #define G_WAIT_V(n) asm volatile("s_waitcnt vmcnt(" #n ")" ::: "memory")
; #define G_BAR __builtin_amdgcn_s_barrier()
; template <class Epi>
; __device__ __forceinline__ void gemm_phase(LAS unsigned char* lds, const bf16_t* Ag, const bf16_t* Btg, const int K, const int nM, const int nN, const Epi& E) {
;     ...
;     for (int i = 0; i < 2; ++i) { int R, C; stage_rc(tid * 16 + i * 8192, R, C); voff[i] = (unsigned)(R * K + C) * 2u; }
;     const size_t kstep = 128, hstep = (size_t)128 * K * 2, tstep = 2 * hstep;
;     const unsigned ldsw = (unsigned)wid * 1024u;
;     const int aoff = lds_byte(wr * 64 + fr, fq * 8), boff = lds_byte(wc * 32 + fr, fq * 8);
;     ...
;     const size_t rstep = (size_t)K * 2;
;     const char* cA = (const char*)Ag + (size_t)prow0(pm) * rstep; const char* cB = (const char*)Btg + (size_t)pn * tstep;
;     E.prep(pm, par, lds);
;     G_STAGE(G_SB(0, 0), cB); G_STAGE(G_SA(0, 0), cA); G_STAGE(G_SB(0, 1), cB + hstep); G_STAGE(G_SA(0, 1), cA + hstep);
;     if (wr == 1) G_BAR;
;     G_WAIT_V(4); G_BAR;
;     G_STAGE(G_SB(1, 0), cB + kstep); G_STAGE(G_SA(1, 0), cA + kstep); G_STAGE(G_SB(1, 1), cB + hstep + kstep);
;     G_WAIT_V(6); G_BAR;
.LBB0_144:
	s_waitcnt vmcnt(8)
	v_bfe_u32 v26, v8, 4, 2
	v_lshl_add_u64 v[18:19], s[66:67], 0, v[0:1]
	v_mov_b32_e32 v3, v1
	v_and_b32_e32 v17, 15, v8
	v_lshlrev_b32_e32 v27, 4, v26
	v_lshlrev_b32_e32 v8, 2, v8
	v_lshl_add_u64 v[20:21], s[66:67], 0, v[2:3]
	s_and_b32 s90, s14, 3
	s_lshl_b32 s26, s12, 6
	v_lshl_or_b32 v27, v17, 6, v27
	s_lshl_b32 s12, s12, 13
	v_and_b32_e32 v8, 32, v8
	s_add_i32 m0, s72, 0x18000
	v_lshl_add_u64 v[18:19], v[18:19], 0, s[94:95]
	v_lshl_add_u64 v[22:23], s[64:65], 0, v[0:1]
	v_bitop3_b32 v28, v27, s12, v8 bitop3:0xde
	s_lshl_b32 s12, s90, 12
	s_waitcnt vmcnt(4)
	s_barrier
	global_load_lds_dwordx4 v[18:19], off
	v_lshl_add_u64 v[18:19], v[20:21], 0, s[94:95]
	s_add_i32 m0, s72, 0x1a000
	s_add_i32 s76, s72, 0x8000
	s_add_i32 s77, s72, 0xa000
	v_lshl_add_u64 v[24:25], s[64:65], 0, v[2:3]
	global_load_lds_dwordx4 v[18:19], off
	v_lshl_add_u64 v[18:19], v[22:23], 0, s[94:95]
	s_mov_b32 m0, s76
	s_add_u32 s14, s66, 0x40080
	global_load_lds_dwordx4 v[18:19], off
	v_lshl_add_u64 v[18:19], v[24:25], 0, s[94:95]
	s_mov_b32 m0, s77
	s_addc_u32 s15, s67, 0
	global_load_lds_dwordx4 v[18:19], off
	s_add_i32 m0, s72, 0x1c000
	v_lshl_add_u64 v[18:19], s[14:15], 0, v[0:1]
	global_load_lds_dwordx4 v[18:19], off
	v_lshl_add_u64 v[18:19], s[14:15], 0, v[2:3]
	s_add_i32 m0, s72, 0x1e000
	v_bitop3_b32 v179, v27, s12, v8 bitop3:0xde
	global_load_lds_dwordx4 v[18:19], off
	v_lshlrev_b32_e32 v8, 2, v26
	v_lshl_or_b32 v222, s90, 5, v8
	v_lshlrev_b32_e32 v8, 13, v13
	v_and_b32_e32 v8, 0x7fffc000, v8
	v_lshl_add_u32 v8, v14, 10, v8
	v_or_b32_e32 v8, v8, v15
	v_add_lshl_u32 v14, v8, v16, 1
	v_lshlrev_b32_e32 v8, 13, v9
	v_and_b32_e32 v8, 0x7fffc000, v8
	v_lshl_add_u32 v8, v10, 10, v8
	v_or_b32_e32 v8, v8, v11
	v_mov_b32_e32 v15, v1
	s_mov_b64 s[14:15], 0x40080
	v_add_lshl_u32 v8, v8, v12, 1
	v_mov_b32_e32 v9, v1
	v_lshl_add_u64 v[136:137], v[14:15], 0, s[14:15]
	v_lshl_add_u64 v[138:139], v[8:9], 0, s[14:15]
	v_readlane_b32 s14, v253, 51
	v_or_b32_e32 v176, s26, v17
	s_waitcnt vmcnt(6)
	s_addk_i32 s26, 0x80
	v_readlane_b32 s15, v253, 52
	v_or_b32_e32 v226, s26, v17
	s_mov_b32 s97, s14
	v_readlane_b32 s14, v255, 21
	v_cmp_eq_u32_e64 s[44:45], 0, v26
	v_or_b32_e32 v223, 16, v176
	v_or_b32_e32 v224, 32, v176
	v_or_b32_e32 v225, 48, v176
	v_or_b32_e32 v227, 16, v226
	v_or_b32_e32 v228, 32, v226
	v_or_b32_e32 v229, 48, v226
	v_mov_b32_e32 v231, 0
	v_add_u32_e32 v230, 0, v28
	v_readlane_b32 s96, v253, 27
	s_mov_b32 s78, s14
	s_barrier
	v_readlane_b32 s15, v255, 22
	s_branch .LBB0_147

; __device__ __forceinline__ int prow0(int pm) { return (pm >> 4) * LP + PADR + (pm & 15) * 256; }
;     __device__ __forceinline__ void prep(int pm, int par, LAS unsigned char* lds) const { if (fold) prep_rowstats(stat, pm, par, lds); }
;     __device__ __forceinline__ void prep(int pm, int par, LAS unsigned char* lds) const { if (!ident) prep_rowstats(stat, pm, par, lds); }
;     __device__ __forceinline__ void prep(int pm, int par, LAS unsigned char* lds) const { prep_rowstats(stat, pm, par, lds); }
; #define G_STAGE(bufoff, gbase) do { _Pragma("unroll") for (int _i = 0; _i < 2; ++_i) \
;         __builtin_amdgcn_global_load_lds((const unsigned*)((const char*)(gbase) + voff[_i]), (LAS unsigned*)(lds + (bufoff) + ldsw + _i * 8192), 16, 0, 0); } while (0)
; #define G_WAIT_V(n) asm volatile("s_waitcnt vmcnt(" #n ")" ::: "memory")
; #define G_BAR __builtin_amdgcn_s_barrier()
; template <class Epi>
; __device__ __forceinline__ void gemm_phase(LAS unsigned char* lds, const bf16_t* Ag, const bf16_t* Btg, const int K, const int nM, const int nN, const Epi& E) {
;     ...
;     for (int i = 0; i < 2; ++i) { int R, C; stage_rc(tid * 16 + i * 8192, R, C); voff[i] = (unsigned)(R * K + C) * 2u; }
;     const size_t kstep = 128, hstep = (size_t)128 * K * 2, tstep = 2 * hstep;
;     const unsigned ldsw = (unsigned)wid * 1024u;
;     const int aoff = lds_byte(wr * 64 + fr, fq * 8), boff = lds_byte(wc * 32 + fr, fq * 8);
;     ...
;     const size_t rstep = (size_t)K * 2;
;     const char* cA = (const char*)Ag + (size_t)prow0(pm) * rstep; const char* cB = (const char*)Btg + (size_t)pn * tstep;
;     E.prep(pm, par, lds);
;     G_STAGE(G_SB(0, 0), cB); G_STAGE(G_SA(0, 0), cA); G_STAGE(G_SB(0, 1), cB + hstep); G_STAGE(G_SA(0, 1), cA + hstep);
;     if (wr == 1) G_BAR;
;     G_WAIT_V(4); G_BAR;
;     G_STAGE(G_SB(1, 0), cB + kstep); G_STAGE(G_SA(1, 0), cA + kstep); G_STAGE(G_SB(1, 1), cB + hstep + kstep);
;     G_WAIT_V(6); G_BAR;
.LBB0_736:
	s_waitcnt vmcnt(8)
	v_bfe_u32 v26, v9, 4, 2
	v_lshl_add_u64 v[18:19], s[58:59], 0, v[0:1]
	v_mov_b32_e32 v3, v1
	v_and_b32_e32 v17, 15, v9
	v_lshlrev_b32_e32 v27, 4, v26
	v_lshlrev_b32_e32 v9, 2, v9
	v_lshl_add_u64 v[20:21], s[58:59], 0, v[2:3]
	s_and_b32 s90, s14, 3
	s_lshl_b32 s24, s12, 6
	v_lshl_or_b32 v27, v17, 6, v27
	s_lshl_b32 s12, s12, 13
	v_and_b32_e32 v9, 32, v9
	s_add_i32 m0, s66, 0x18000
	v_lshl_add_u64 v[18:19], v[18:19], 0, s[94:95]
	v_lshl_add_u64 v[22:23], s[56:57], 0, v[0:1]
	v_bitop3_b32 v28, v27, s12, v9 bitop3:0xde
	s_lshl_b32 s12, s90, 12
	s_waitcnt vmcnt(4)
	s_barrier
	global_load_lds_dwordx4 v[18:19], off
	v_lshl_add_u64 v[18:19], v[20:21], 0, s[94:95]
	s_add_i32 m0, s66, 0x1a000
	s_add_i32 s70, s66, 0x8000
	s_add_i32 s71, s66, 0xa000
	v_lshl_add_u64 v[24:25], s[56:57], 0, v[2:3]
	global_load_lds_dwordx4 v[18:19], off
	v_lshl_add_u64 v[18:19], v[22:23], 0, s[94:95]
	s_mov_b32 m0, s70
	s_add_u32 s14, s58, 0x100080
	global_load_lds_dwordx4 v[18:19], off
	v_lshl_add_u64 v[18:19], v[24:25], 0, s[94:95]
	s_mov_b32 m0, s71
	s_addc_u32 s15, s59, 0
	global_load_lds_dwordx4 v[18:19], off
	s_add_i32 m0, s66, 0x1c000
	v_lshl_add_u64 v[18:19], s[14:15], 0, v[0:1]
	global_load_lds_dwordx4 v[18:19], off
	v_lshl_add_u64 v[18:19], s[14:15], 0, v[2:3]
	s_add_i32 m0, s66, 0x1e000
	v_bitop3_b32 v165, v27, s12, v9 bitop3:0xde
	global_load_lds_dwordx4 v[18:19], off
	v_lshlrev_b32_e32 v9, 2, v26
	v_lshl_or_b32 v166, s90, 5, v9
	v_lshlrev_b32_e32 v9, 15, v13
	v_lshlrev_b32_e32 v8, 15, v8
	v_and_b32_e32 v9, 0x7fff0000, v9
	v_and_b32_e32 v8, 0x7fff0000, v8
	v_lshl_add_u32 v9, v14, 12, v9
	v_lshl_add_u32 v8, v10, 12, v8
	v_or_b32_e32 v9, v9, v15
	v_or_b32_e32 v8, v8, v11
	v_add_lshl_u32 v14, v9, v16, 1
	v_mov_b32_e32 v15, v1
	s_mov_b64 s[14:15], 0x100080
	v_add_lshl_u32 v8, v8, v12, 1
	v_mov_b32_e32 v9, v1
	v_lshl_add_u64 v[136:137], v[14:15], 0, s[14:15]
	v_lshl_add_u64 v[138:139], v[8:9], 0, s[14:15]
	v_readlane_b32 s14, v253, 51
	v_or_b32_e32 v164, s24, v17
	s_waitcnt vmcnt(6)
	s_addk_i32 s24, 0x80
	v_readlane_b32 s15, v253, 52
	v_or_b32_e32 v170, s24, v17
	s_mov_b32 s76, s14
	v_readlane_b32 s14, v255, 21
	s_mov_b32 s72, 0
	v_cmp_eq_u32_e64 s[44:45], 0, v26
	v_or_b32_e32 v167, 16, v164
	v_or_b32_e32 v168, 32, v164
	v_or_b32_e32 v169, 48, v164
	v_or_b32_e32 v171, 16, v170
	v_or_b32_e32 v172, 32, v170
	v_or_b32_e32 v173, 48, v170
	v_add_u32_e32 v174, 0, v28
	v_readlane_b32 s74, v253, 27
	s_mov_b32 s73, s14
	s_barrier
	v_readlane_b32 s15, v255, 22
	s_branch .LBB0_738
